# attnA: V fragment reads issued at head of previous P.V block, K reads before DMA issue at step start
# speedup vs baseline: 1.0250x; 1.0072x over previous
; #define LAS __attribute__((address_space(3)))
; __device__ __forceinline__ float fexp2(float x) { return __builtin_amdgcn_exp2f(x); }
; #define MFMA32(a, b, c) __builtin_amdgcn_mfma_f32_32x32x16_bf16((a), (b), (c), 0, 0, 0)
; __device__ __forceinline__ bf16x8 v_build(const VRaw& r, int ks) { return (bf16x8){r.lo[ks][0], r.lo[ks][1], r.lo[ks][2], r.lo[ks][3], r.hv[ks][0], r.hv[ks][1], r.hv[ks][2], r.hv[ks][3]}; }
; #define SB_ __builtin_amdgcn_sched_barrier(0)
; #define A_MAX() \
;         float mx = fmaxf(s[0][0], s[1][0]); \
;         _Pragma("unroll") for (int r = 1; r < 16; ++r) mx = fmaxf(fmaxf(mx, s[0][r]), s[1][r]); \
;         mx = fmaxf(mx, __shfl_xor(mx, 32));
; __device__ __forceinline__ void attnA_unit(const P2Ctx& C, int b, int h, int qb) {
;     ...
;     for (int kt = 1; kt < NT; ++kt) {
;         if (kt + 2 < NT && !(pf & 16)) A_DMA(kt + 2);
;         if (kt < ntw) {
;             A_QK(kt)
;             if (!(pf & 4)) {
;             const LAS unsigned char* vimg = lds + ((kt - 1) & 3) * 32768 + 16384;
;             VRaw va;
;             v_issue<4>(vimg, 0, lane, va);
;             A_MAX()
;             float fres = 1.0f; bool resc = false;
;             if (__any(mx > ATHR)) {
;                 const float dl = fmaxf(mx, 0.f);
;                 mhat += dl;
;                 fres = fexp2(-dl); resc = true;
; #pragma unroll
;                 for (int kb2 = 0; kb2 < 2; ++kb2)
; #pragma unroll
;                     for (int r = 0; r < 16; ++r) s[kb2][r] -= dl;
;             }
;             float ps = 0.f;
;             v_wait(va);
;             __builtin_amdgcn_s_setprio(1);
; #pragma unroll
;             for (int ks = 0; ks < 4; ++ks) o[0] = MFMA32(v_build(va, ks), pf_[ks], o[0]);
;             EX4_(s[0], 0); EX4_(s[0], 4); EX4_(s[0], 8); EX4_(s[0], 12);
;             SB_; v_issue<4>(vimg, 1, lane, va); v_wait(va);
; #pragma unroll
;             for (int ks = 0; ks < 4; ++ks) o[1] = MFMA32(v_build(va, ks), pf_[ks], o[1]);
;             EX4_(s[1], 0); EX4_(s[1], 4); EX4_(s[1], 8); EX4_(s[1], 12);
;             SB_; v_issue<4>(vimg, 2, lane, va); v_wait(va);
; #pragma unroll
;             for (int ks = 0; ks < 4; ++ks) o[2] = MFMA32(v_build(va, ks), pf_[ks], o[2]);
;             SUM8_(s[0], 0); SUM8_(s[0], 8); SUM8_(s[1], 0); SUM8_(s[1], 8);
;             SB_; v_issue<4>(vimg, 3, lane, va); v_wait(va);
.LaA_loop:
	s_cmp_lt_u32 s14, s13
	s_cbranch_scc0 .LaA_pvonly
	s_and_b32 s6, s14, 3
	s_lshl_b32 s6, s6, 15
	s_add_i32 s7, s14, -1
	s_and_b32 s7, s7, 3
	s_lshl_b32 s7, s7, 15
	v_add_u32_e32 v248, s6, v200
	v_add_u32_e32 v249, s6, v201
	v_add_u32_e32 v250, s6, v202
	v_add_u32_e32 v251, s6, v203
	v_add_u32_e32 v237, s7, v204
	ds_read_b128 v[100:103], v248
	ds_read_b128 v[104:107], v248 offset:4096
	ds_read_b128 v[108:111], v249
	ds_read_b128 v[112:115], v249 offset:4096
	ds_read_b128 v[116:119], v250
	ds_read_b128 v[120:123], v250 offset:4096
	ds_read_b128 v[124:127], v251
	ds_read_b128 v[128:131], v251 offset:4096
	s_cmp_lt_u32 s24, s12
	s_cbranch_scc0 .LaA_nodma_7
	s_and_b32 s6, s24, 3
	s_lshl_b32 s6, s6, 15
	s_add_i32 s7, s6, s22
	s_mov_b32 m0, s7
	s_add_u32 s20, s16, 0x80
	s_addc_u32 s21, s17, 0
	s_add_i32 s29, s6, s23
	global_load_lds_dwordx4 v197, s[16:17]
	s_add_i32 m0, s7, 0x2000
	s_add_u32 s16, s16, 0x20000
	s_addc_u32 s17, s17, 0
	s_nop 0
	global_load_lds_dwordx4 v197, s[20:21]
	s_mov_b32 m0, s29
	s_add_u32 s20, s18, 0x80
	s_addc_u32 s21, s19, 0
	s_nop 0
	global_load_lds_dwordx4 v198, s[18:19]
	s_add_i32 m0, s29, 0x400
	s_add_u32 s18, s18, 0x20000
	s_addc_u32 s19, s19, 0
	s_add_i32 s24, s24, 1
	global_load_lds_dwordx4 v198, s[20:21]
.LaA_nodma_7:
	s_waitcnt lgkmcnt(7)
	v_mfma_f32_32x32x16_bf16 v[68:83], v[100:103], v[164:167], v[220:235]
	ds_read_b64_tr_b16 v[132:133], v237 offset:0
	ds_read_b64_tr_b16 v[134:135], v237 offset:2048
	s_waitcnt lgkmcnt(8)
	v_mfma_f32_32x32x16_bf16 v[84:99], v[104:107], v[164:167], v[220:235]
	ds_read_b64_tr_b16 v[136:137], v237 offset:4096
	ds_read_b64_tr_b16 v[138:139], v237 offset:6144
	s_waitcnt lgkmcnt(9)
	v_mfma_f32_32x32x16_bf16 v[68:83], v[108:111], v[168:171], v[68:83]
	ds_read_b64_tr_b16 v[140:141], v237 offset:8192
	ds_read_b64_tr_b16 v[142:143], v237 offset:10240
	s_waitcnt lgkmcnt(10)
	v_mfma_f32_32x32x16_bf16 v[84:99], v[112:115], v[168:171], v[84:99]
	ds_read_b64_tr_b16 v[144:145], v237 offset:12288
	ds_read_b64_tr_b16 v[146:147], v237 offset:14336
	s_waitcnt lgkmcnt(11)
	v_mfma_f32_32x32x16_bf16 v[68:83], v[116:119], v[172:175], v[68:83]
	s_waitcnt lgkmcnt(10)
	v_mfma_f32_32x32x16_bf16 v[84:99], v[120:123], v[172:175], v[84:99]
	s_waitcnt lgkmcnt(9)
	v_mfma_f32_32x32x16_bf16 v[68:83], v[124:127], v[176:179], v[68:83]
	s_waitcnt lgkmcnt(8)
	v_mfma_f32_32x32x16_bf16 v[84:99], v[128:131], v[176:179], v[84:99]
	s_waitcnt lgkmcnt(0)
	ds_read_b64_tr_b16 v[148:149], v237 offset:512
	ds_read_b64_tr_b16 v[150:151], v237 offset:2560
	v_mfma_f32_32x32x16_bf16 v[4:19], v[132:135], v[180:183], v[4:19]
	ds_read_b64_tr_b16 v[152:153], v237 offset:4608
	ds_read_b64_tr_b16 v[154:155], v237 offset:6656
	ds_read_b64_tr_b16 v[156:157], v237 offset:8704
	v_mfma_f32_32x32x16_bf16 v[4:19], v[136:139], v[184:187], v[4:19]
	ds_read_b64_tr_b16 v[158:159], v237 offset:10752
	ds_read_b64_tr_b16 v[160:161], v237 offset:12800
	ds_read_b64_tr_b16 v[162:163], v237 offset:14848
	v_mfma_f32_32x32x16_bf16 v[4:19], v[140:143], v[188:191], v[4:19]
	v_mfma_f32_32x32x16_bf16 v[4:19], v[144:147], v[192:195], v[4:19]
	s_lshl_b32 s6, s14, 6
	s_cmp_gt_i32 s6, s26
	s_cbranch_scc1 .LaA_near_8
.LaA_far_9:
	s_waitcnt lgkmcnt(0)
	ds_read_b64_tr_b16 v[132:133], v237 offset:1024
	ds_read_b64_tr_b16 v[134:135], v237 offset:3072
	v_mfma_f32_32x32x16_bf16 v[20:35], v[148:151], v[180:183], v[20:35]
	ds_read_b64_tr_b16 v[136:137], v237 offset:5120
	ds_read_b64_tr_b16 v[138:139], v237 offset:7168
	ds_read_b64_tr_b16 v[140:141], v237 offset:9216
	v_max_f32_e32 v242, v68, v69
	v_max_f32_e32 v243, v84, v85
	v_max3_f32 v242, v242, v70, v71
	v_max3_f32 v243, v243, v86, v87
	v_max3_f32 v242, v242, v72, v73
	v_mfma_f32_32x32x16_bf16 v[20:35], v[152:155], v[184:187], v[20:35]
	ds_read_b64_tr_b16 v[142:143], v237 offset:11264
	ds_read_b64_tr_b16 v[144:145], v237 offset:13312
	ds_read_b64_tr_b16 v[146:147], v237 offset:15360
	v_max3_f32 v243, v243, v88, v89
	v_max3_f32 v242, v242, v74, v75
	v_max3_f32 v243, v243, v90, v91
	v_max3_f32 v242, v242, v76, v77
	v_max3_f32 v243, v243, v92, v93
	v_mfma_f32_32x32x16_bf16 v[20:35], v[156:159], v[188:191], v[20:35]
	v_max3_f32 v242, v242, v78, v79
	v_max3_f32 v243, v243, v94, v95
	v_max3_f32 v242, v242, v80, v81
	v_max3_f32 v243, v243, v96, v97
	v_max3_f32 v242, v242, v82, v83
	v_mfma_f32_32x32x16_bf16 v[20:35], v[160:163], v[192:195], v[20:35]
	v_max3_f32 v243, v243, v98, v99
	v_max_f32_e32 v242, v242, v243
	v_mov_b32_e32 v243, v242
	s_nop 1
	v_permlane32_swap_b32 v243, v242
	v_max_f32_e32 v247, v243, v242
	v_cmp_lt_f32_e32 vcc, 0x41000000, v247
	s_cmp_lg_u64 vcc, 0
	s_cbranch_scc1 .LaA_resc_pre
; #define MFMA32(a, b, c) __builtin_amdgcn_mfma_f32_32x32x16_bf16((a), (b), (c), 0, 0, 0)
; __device__ __forceinline__ bf16x8 v_build(const VRaw& r, int ks) { return (bf16x8){r.lo[ks][0], r.lo[ks][1], r.lo[ks][2], r.lo[ks][3], r.hv[ks][0], r.hv[ks][1], r.hv[ks][2], r.hv[ks][3]}; }
; #define SB_ __builtin_amdgcn_sched_barrier(0)
; #define EX4_(S, B) do { S[B] = fexp2(S[B]); S[B + 1] = fexp2(S[B + 1]); S[B + 2] = fexp2(S[B + 2]); S[B + 3] = fexp2(S[B + 3]); } while (0)
; #define SUM8_(S, B) do { ps += ((S[B] + S[B + 1]) + (S[B + 2] + S[B + 3])) + ((S[B + 4] + S[B + 5]) + (S[B + 6] + S[B + 7])); } while (0)
; __device__ __forceinline__ void attnA_unit(const P2Ctx& C, int b, int h, int qb) {
;     ...
;             v_wait(va);
;             __builtin_amdgcn_s_setprio(1);
; #pragma unroll
;             for (int ks = 0; ks < 4; ++ks) o[0] = MFMA32(v_build(va, ks), pf_[ks], o[0]);
;             EX4_(s[0], 0); EX4_(s[0], 4); EX4_(s[0], 8); EX4_(s[0], 12);
;             SB_; v_issue<4>(vimg, 1, lane, va); v_wait(va);
; #pragma unroll
;             for (int ks = 0; ks < 4; ++ks) o[1] = MFMA32(v_build(va, ks), pf_[ks], o[1]);
;             EX4_(s[1], 0); EX4_(s[1], 4); EX4_(s[1], 8); EX4_(s[1], 12);
;             SB_; v_issue<4>(vimg, 2, lane, va); v_wait(va);
; #pragma unroll
;             for (int ks = 0; ks < 4; ++ks) o[2] = MFMA32(v_build(va, ks), pf_[ks], o[2]);
;             SUM8_(s[0], 0); SUM8_(s[0], 8); SUM8_(s[1], 0); SUM8_(s[1], 8);
;             SB_; v_issue<4>(vimg, 3, lane, va); v_wait(va);
;             o[3] = MFMA32(v_build(va, 0), pf_[0], o[3]); pf_[0] = pack_p(s[0], 0);
;             o[3] = MFMA32(v_build(va, 1), pf_[1], o[3]); pf_[1] = pack_p(s[0], 1);
;             o[3] = MFMA32(v_build(va, 2), pf_[2], o[3]); pf_[2] = pack_p(s[1], 0);
;             o[3] = MFMA32(v_build(va, 3), pf_[3], o[3]); pf_[3] = pack_p(s[1], 1);
;             __builtin_amdgcn_s_setprio(0);
.LaA_resc_back:
	s_waitcnt lgkmcnt(0)
	ds_read_b64_tr_b16 v[148:149], v237 offset:1536
	ds_read_b64_tr_b16 v[150:151], v237 offset:3584
	v_mfma_f32_32x32x16_bf16 v[36:51], v[132:135], v[180:183], v[36:51]
	ds_read_b64_tr_b16 v[152:153], v237 offset:5632
	ds_read_b64_tr_b16 v[154:155], v237 offset:7680
	ds_read_b64_tr_b16 v[156:157], v237 offset:9728
	v_exp_f32_e32 v68, v68
	v_exp_f32_e32 v69, v69
	v_exp_f32_e32 v70, v70
	v_exp_f32_e32 v71, v71
	v_mfma_f32_32x32x16_bf16 v[36:51], v[136:139], v[184:187], v[36:51]
	ds_read_b64_tr_b16 v[158:159], v237 offset:11776
	ds_read_b64_tr_b16 v[160:161], v237 offset:13824
	ds_read_b64_tr_b16 v[162:163], v237 offset:15872
	v_exp_f32_e32 v72, v72
	v_exp_f32_e32 v73, v73
	v_exp_f32_e32 v74, v74
	v_exp_f32_e32 v75, v75
	v_mfma_f32_32x32x16_bf16 v[36:51], v[140:143], v[188:191], v[36:51]
	v_exp_f32_e32 v76, v76
	v_exp_f32_e32 v77, v77
	v_exp_f32_e32 v78, v78
	v_exp_f32_e32 v79, v79
	v_mfma_f32_32x32x16_bf16 v[36:51], v[144:147], v[192:195], v[36:51]
	v_exp_f32_e32 v80, v80
	v_exp_f32_e32 v81, v81
	v_exp_f32_e32 v82, v82
	v_exp_f32_e32 v83, v83
	s_waitcnt lgkmcnt(0)
	v_mfma_f32_32x32x16_bf16 v[52:67], v[148:151], v[180:183], v[52:67]
	v_exp_f32_e32 v84, v84
	v_exp_f32_e32 v85, v85
	v_exp_f32_e32 v86, v86
	v_exp_f32_e32 v87, v87
	v_exp_f32_e32 v88, v88
	v_exp_f32_e32 v89, v89
	v_exp_f32_e32 v90, v90
	v_exp_f32_e32 v91, v91
	v_cvt_pk_bf16_f32 v180, v68, v69
	v_cvt_pk_bf16_f32 v181, v70, v71
	v_cvt_pk_bf16_f32 v182, v72, v73
	v_cvt_pk_bf16_f32 v183, v74, v75
	v_mfma_f32_32x32x16_bf16 v[52:67], v[152:155], v[184:187], v[52:67]
	v_exp_f32_e32 v92, v92
	v_exp_f32_e32 v93, v93
	v_exp_f32_e32 v94, v94
	v_exp_f32_e32 v95, v95
	v_exp_f32_e32 v96, v96
	v_exp_f32_e32 v97, v97
	v_exp_f32_e32 v98, v98
	v_exp_f32_e32 v99, v99
	v_cvt_pk_bf16_f32 v184, v76, v77
	v_cvt_pk_bf16_f32 v185, v78, v79
	v_cvt_pk_bf16_f32 v186, v80, v81
	v_cvt_pk_bf16_f32 v187, v82, v83
	v_mfma_f32_32x32x16_bf16 v[52:67], v[156:159], v[188:191], v[52:67]
	v_add_f32_e32 v245, v68, v69
	v_add_f32_e32 v243, v70, v71
	v_add_f32_e32 v245, v245, v243
	v_add_f32_e32 v243, v72, v73
	v_add_f32_e32 v242, v74, v75
	v_add_f32_e32 v243, v243, v242
	v_add_f32_e32 v245, v245, v243
	v_add_f32_e32 v246, v76, v77
	v_add_f32_e32 v243, v78, v79
	v_add_f32_e32 v246, v246, v243
	v_add_f32_e32 v243, v80, v81
	v_add_f32_e32 v242, v82, v83
	v_add_f32_e32 v243, v243, v242
	v_add_f32_e32 v246, v246, v243
	v_add_f32_e32 v245, v245, v246
	v_cvt_pk_bf16_f32 v188, v84, v85
	v_cvt_pk_bf16_f32 v189, v86, v87
	v_cvt_pk_bf16_f32 v190, v88, v89
	v_cvt_pk_bf16_f32 v191, v90, v91
	v_mfma_f32_32x32x16_bf16 v[52:67], v[160:163], v[192:195], v[52:67]
	v_add_f32_e32 v246, v84, v85
	v_add_f32_e32 v243, v86, v87
	v_add_f32_e32 v246, v246, v243
	v_add_f32_e32 v243, v88, v89
	v_add_f32_e32 v242, v90, v91
	v_add_f32_e32 v243, v243, v242
	v_add_f32_e32 v246, v246, v243
	v_add_f32_e32 v245, v245, v246
	v_add_f32_e32 v246, v92, v93
	v_add_f32_e32 v243, v94, v95
	v_add_f32_e32 v246, v246, v243
	v_add_f32_e32 v243, v96, v97
	v_add_f32_e32 v242, v98, v99
	v_add_f32_e32 v243, v243, v242
	v_add_f32_e32 v246, v246, v243
	v_add_f32_e32 v245, v245, v246
	v_cvt_pk_bf16_f32 v192, v92, v93
	v_cvt_pk_bf16_f32 v193, v94, v95
	v_cvt_pk_bf16_f32 v194, v96, v97
	v_cvt_pk_bf16_f32 v195, v98, v99
	s_cmp_lg_u32 s25, 0
	s_cbranch_scc1 .LaA_resc_post

; __device__ __forceinline__ void attnA_unit(const P2Ctx& C, int b, int h, int qb) {
;     ...
;     f32x16 o[4];
; #pragma unroll
;     for (int cb = 0; cb < 4; ++cb)
; #pragma unroll
;         for (int r = 0; r < 16; ++r) o[cb][r] = 0.f;
;     float mhat = 0.f, l = 0.f;
;     bf16x8 pf_[4];
; #pragma unroll
;     for (int i = 0; i < 4; ++i) pf_[i] = (bf16x8){0, 0, 0, 0, 0, 0, 0, 0};
;     ...
;             if (resc) {
;                 l *= fres;
; #pragma unroll
;                 for (int cb = 0; cb < 4; ++cb)
; #pragma unroll
;                     for (int r = 0; r < 16; ++r) o[cb][r] *= fres;
;             }
;             l += ps;
;             }
;         } else if (kt - 1 < ntw && !(pf & 2)) { A_PV(kt - 1); }
.LaA_resc_post:
	s_nop 7
	s_nop 3
	v_mul_f32_e32 v4, v244, v4
	v_mul_f32_e32 v5, v244, v5
	v_mul_f32_e32 v6, v244, v6
	v_mul_f32_e32 v7, v244, v7
	v_mul_f32_e32 v8, v244, v8
	v_mul_f32_e32 v9, v244, v9
	v_mul_f32_e32 v10, v244, v10
	v_mul_f32_e32 v11, v244, v11
	v_mul_f32_e32 v12, v244, v12
	v_mul_f32_e32 v13, v244, v13
	v_mul_f32_e32 v14, v244, v14
	v_mul_f32_e32 v15, v244, v15
	v_mul_f32_e32 v16, v244, v16
	v_mul_f32_e32 v17, v244, v17
	v_mul_f32_e32 v18, v244, v18
	v_mul_f32_e32 v19, v244, v19
	v_mul_f32_e32 v20, v244, v20
	v_mul_f32_e32 v21, v244, v21
	v_mul_f32_e32 v22, v244, v22
	v_mul_f32_e32 v23, v244, v23
	v_mul_f32_e32 v24, v244, v24
	v_mul_f32_e32 v25, v244, v25
	v_mul_f32_e32 v26, v244, v26
	v_mul_f32_e32 v27, v244, v27
	v_mul_f32_e32 v28, v244, v28
	v_mul_f32_e32 v29, v244, v29
	v_mul_f32_e32 v30, v244, v30
	v_mul_f32_e32 v31, v244, v31
	v_mul_f32_e32 v32, v244, v32
	v_mul_f32_e32 v33, v244, v33
	v_mul_f32_e32 v34, v244, v34
	v_mul_f32_e32 v35, v244, v35
	v_mul_f32_e32 v36, v244, v36
	v_mul_f32_e32 v37, v244, v37
	v_mul_f32_e32 v38, v244, v38
	v_mul_f32_e32 v39, v244, v39
	v_mul_f32_e32 v40, v244, v40
	v_mul_f32_e32 v41, v244, v41
	v_mul_f32_e32 v42, v244, v42
	v_mul_f32_e32 v43, v244, v43
	v_mul_f32_e32 v44, v244, v44
	v_mul_f32_e32 v45, v244, v45
	v_mul_f32_e32 v46, v244, v46
	v_mul_f32_e32 v47, v244, v47
	v_mul_f32_e32 v48, v244, v48
	v_mul_f32_e32 v49, v244, v49
	v_mul_f32_e32 v50, v244, v50
	v_mul_f32_e32 v51, v244, v51
	v_mul_f32_e32 v52, v244, v52
	v_mul_f32_e32 v53, v244, v53
	v_mul_f32_e32 v54, v244, v54
	v_mul_f32_e32 v55, v244, v55
	v_mul_f32_e32 v56, v244, v56
	v_mul_f32_e32 v57, v244, v57
	v_mul_f32_e32 v58, v244, v58
	v_mul_f32_e32 v59, v244, v59
	v_mul_f32_e32 v60, v244, v60
	v_mul_f32_e32 v61, v244, v61
	v_mul_f32_e32 v62, v244, v62
	v_mul_f32_e32 v63, v244, v63
	v_mul_f32_e32 v64, v244, v64
	v_mul_f32_e32 v65, v244, v65
	v_mul_f32_e32 v66, v244, v66
	v_mul_f32_e32 v67, v244, v67
	v_mul_f32_e32 v241, v244, v241
	s_mov_b32 s25, 0
	s_branch .LaA_resc_done
.LaA_pvonly:
	s_cmp_lt_u32 s24, s12
	s_cbranch_scc0 .LaA_nodma_13
	s_and_b32 s6, s24, 3
	s_lshl_b32 s6, s6, 15
	s_add_i32 s7, s6, s22
	s_mov_b32 m0, s7
	s_add_u32 s20, s16, 0x80
	s_addc_u32 s21, s17, 0
	s_add_i32 s29, s6, s23
	global_load_lds_dwordx4 v197, s[16:17]
	s_add_i32 m0, s7, 0x2000
	s_add_u32 s16, s16, 0x20000
	s_addc_u32 s17, s17, 0
	s_nop 0
	global_load_lds_dwordx4 v197, s[20:21]
	s_mov_b32 m0, s29
	s_add_u32 s20, s18, 0x80
	s_addc_u32 s21, s19, 0
	s_nop 0
	global_load_lds_dwordx4 v198, s[18:19]
	s_add_i32 m0, s29, 0x400
	s_add_u32 s18, s18, 0x20000
	s_addc_u32 s19, s19, 0
	s_add_i32 s24, s24, 1
	global_load_lds_dwordx4 v198, s[20:21]
.LaA_nodma_13:
	s_cmp_eq_u32 s14, s13
	s_cbranch_scc0 .LaA_pvskip_12
	s_add_i32 s7, s14, -1
	s_and_b32 s7, s7, 3
	s_lshl_b32 s7, s7, 15
	v_add_u32_e32 v237, s7, v204
	ds_read_b64_tr_b16 v[132:133], v237 offset:0
	ds_read_b64_tr_b16 v[134:135], v237 offset:2048
	ds_read_b64_tr_b16 v[136:137], v237 offset:4096
	ds_read_b64_tr_b16 v[138:139], v237 offset:6144
	ds_read_b64_tr_b16 v[140:141], v237 offset:8192
	ds_read_b64_tr_b16 v[142:143], v237 offset:10240
	ds_read_b64_tr_b16 v[144:145], v237 offset:12288
	ds_read_b64_tr_b16 v[146:147], v237 offset:14336
	s_waitcnt lgkmcnt(0)
	ds_read_b64_tr_b16 v[148:149], v237 offset:512
	ds_read_b64_tr_b16 v[150:151], v237 offset:2560
	v_mfma_f32_32x32x16_bf16 v[4:19], v[132:135], v[180:183], v[4:19]
	ds_read_b64_tr_b16 v[152:153], v237 offset:4608
	ds_read_b64_tr_b16 v[154:155], v237 offset:6656
	ds_read_b64_tr_b16 v[156:157], v237 offset:8704
	v_mfma_f32_32x32x16_bf16 v[4:19], v[136:139], v[184:187], v[4:19]
	ds_read_b64_tr_b16 v[158:159], v237 offset:10752
	ds_read_b64_tr_b16 v[160:161], v237 offset:12800
	ds_read_b64_tr_b16 v[162:163], v237 offset:14848
	v_mfma_f32_32x32x16_bf16 v[4:19], v[140:143], v[188:191], v[4:19]
	v_mfma_f32_32x32x16_bf16 v[4:19], v[144:147], v[192:195], v[4:19]
	s_waitcnt lgkmcnt(0)
	ds_read_b64_tr_b16 v[132:133], v237 offset:1024
	ds_read_b64_tr_b16 v[134:135], v237 offset:3072
	v_mfma_f32_32x32x16_bf16 v[20:35], v[148:151], v[180:183], v[20:35]
	ds_read_b64_tr_b16 v[136:137], v237 offset:5120
	ds_read_b64_tr_b16 v[138:139], v237 offset:7168
	ds_read_b64_tr_b16 v[140:141], v237 offset:9216
	v_mfma_f32_32x32x16_bf16 v[20:35], v[152:155], v[184:187], v[20:35]
	ds_read_b64_tr_b16 v[142:143], v237 offset:11264
	ds_read_b64_tr_b16 v[144:145], v237 offset:13312
	ds_read_b64_tr_b16 v[146:147], v237 offset:15360
	v_mfma_f32_32x32x16_bf16 v[20:35], v[156:159], v[188:191], v[20:35]
	v_mfma_f32_32x32x16_bf16 v[20:35], v[160:163], v[192:195], v[20:35]
	s_waitcnt lgkmcnt(0)
	ds_read_b64_tr_b16 v[148:149], v237 offset:1536
	ds_read_b64_tr_b16 v[150:151], v237 offset:3584
	v_mfma_f32_32x32x16_bf16 v[36:51], v[132:135], v[180:183], v[36:51]
	ds_read_b64_tr_b16 v[152:153], v237 offset:5632
	ds_read_b64_tr_b16 v[154:155], v237 offset:7680
	ds_read_b64_tr_b16 v[156:157], v237 offset:9728
	v_mfma_f32_32x32x16_bf16 v[36:51], v[136:139], v[184:187], v[36:51]
	ds_read_b64_tr_b16 v[158:159], v237 offset:11776
	ds_read_b64_tr_b16 v[160:161], v237 offset:13824
	ds_read_b64_tr_b16 v[162:163], v237 offset:15872
	v_mfma_f32_32x32x16_bf16 v[36:51], v[140:143], v[188:191], v[36:51]
	v_mfma_f32_32x32x16_bf16 v[36:51], v[144:147], v[192:195], v[36:51]
	s_waitcnt lgkmcnt(0)
	v_mfma_f32_32x32x16_bf16 v[52:67], v[148:151], v[180:183], v[52:67]
	v_mfma_f32_32x32x16_bf16 v[52:67], v[152:155], v[184:187], v[52:67]
	v_mfma_f32_32x32x16_bf16 v[52:67], v[156:159], v[188:191], v[52:67]
	v_mfma_f32_32x32x16_bf16 v[52:67], v[160:163], v[192:195], v[52:67]

; #define LAS __attribute__((address_space(3)))
; __device__ __forceinline__ void attnA_unit(const P2Ctx& C, int b, int h, int qb) {
;     ...
;     if (NT - 1 < ntw && !(pf & 2)) A_PV(NT - 1);
;     __syncthreads();
;     ...
;     l += __shfl_xor(l, 32);
;     const float inv = 1.0f / l;
;     LAS float* X2 = (LAS float*)(lds + 65536);
;     if (comp == 1) {
; #pragma unroll
;         for (int cb = 0; cb < 4; ++cb)
; #pragma unroll
;             for (int r = 0; r < 16; ++r) X2[((qs * 4 + cb) * 16 + r) * 64 + lane] = o[cb][r] * inv;
;     }
.LaA_loopexit:
	s_cmp_eq_u32 s13, s12
	s_cbranch_scc0 .LaA_nofinalpv_14
	s_add_i32 s7, s14, -1
	s_and_b32 s7, s7, 3
	s_lshl_b32 s7, s7, 15
	v_add_u32_e32 v237, s7, v204
	ds_read_b64_tr_b16 v[132:133], v237 offset:0
	ds_read_b64_tr_b16 v[134:135], v237 offset:2048
	ds_read_b64_tr_b16 v[136:137], v237 offset:4096
	ds_read_b64_tr_b16 v[138:139], v237 offset:6144
	ds_read_b64_tr_b16 v[140:141], v237 offset:8192
	ds_read_b64_tr_b16 v[142:143], v237 offset:10240
	ds_read_b64_tr_b16 v[144:145], v237 offset:12288
	ds_read_b64_tr_b16 v[146:147], v237 offset:14336
	s_waitcnt lgkmcnt(0)
	ds_read_b64_tr_b16 v[148:149], v237 offset:512
	ds_read_b64_tr_b16 v[150:151], v237 offset:2560
	v_mfma_f32_32x32x16_bf16 v[4:19], v[132:135], v[180:183], v[4:19]
	ds_read_b64_tr_b16 v[152:153], v237 offset:4608
	ds_read_b64_tr_b16 v[154:155], v237 offset:6656
	ds_read_b64_tr_b16 v[156:157], v237 offset:8704
	v_mfma_f32_32x32x16_bf16 v[4:19], v[136:139], v[184:187], v[4:19]
	ds_read_b64_tr_b16 v[158:159], v237 offset:10752
	ds_read_b64_tr_b16 v[160:161], v237 offset:12800
	ds_read_b64_tr_b16 v[162:163], v237 offset:14848
	v_mfma_f32_32x32x16_bf16 v[4:19], v[140:143], v[188:191], v[4:19]
	v_mfma_f32_32x32x16_bf16 v[4:19], v[144:147], v[192:195], v[4:19]
	s_waitcnt lgkmcnt(0)
	ds_read_b64_tr_b16 v[132:133], v237 offset:1024
	ds_read_b64_tr_b16 v[134:135], v237 offset:3072
	v_mfma_f32_32x32x16_bf16 v[20:35], v[148:151], v[180:183], v[20:35]
	ds_read_b64_tr_b16 v[136:137], v237 offset:5120
	ds_read_b64_tr_b16 v[138:139], v237 offset:7168
	ds_read_b64_tr_b16 v[140:141], v237 offset:9216
	v_mfma_f32_32x32x16_bf16 v[20:35], v[152:155], v[184:187], v[20:35]
	ds_read_b64_tr_b16 v[142:143], v237 offset:11264
	ds_read_b64_tr_b16 v[144:145], v237 offset:13312
	ds_read_b64_tr_b16 v[146:147], v237 offset:15360
	v_mfma_f32_32x32x16_bf16 v[20:35], v[156:159], v[188:191], v[20:35]
	v_mfma_f32_32x32x16_bf16 v[20:35], v[160:163], v[192:195], v[20:35]
	s_waitcnt lgkmcnt(0)
	ds_read_b64_tr_b16 v[148:149], v237 offset:1536
	ds_read_b64_tr_b16 v[150:151], v237 offset:3584
	v_mfma_f32_32x32x16_bf16 v[36:51], v[132:135], v[180:183], v[36:51]
	ds_read_b64_tr_b16 v[152:153], v237 offset:5632
	ds_read_b64_tr_b16 v[154:155], v237 offset:7680
	ds_read_b64_tr_b16 v[156:157], v237 offset:9728
	v_mfma_f32_32x32x16_bf16 v[36:51], v[136:139], v[184:187], v[36:51]
	ds_read_b64_tr_b16 v[158:159], v237 offset:11776
	ds_read_b64_tr_b16 v[160:161], v237 offset:13824
	ds_read_b64_tr_b16 v[162:163], v237 offset:15872
	v_mfma_f32_32x32x16_bf16 v[36:51], v[140:143], v[188:191], v[36:51]
	v_mfma_f32_32x32x16_bf16 v[36:51], v[144:147], v[192:195], v[36:51]
	s_waitcnt lgkmcnt(0)
	v_mfma_f32_32x32x16_bf16 v[52:67], v[148:151], v[180:183], v[52:67]
	v_mfma_f32_32x32x16_bf16 v[52:67], v[152:155], v[184:187], v[52:67]
	v_mfma_f32_32x32x16_bf16 v[52:67], v[156:159], v[188:191], v[52:67]
	v_mfma_f32_32x32x16_bf16 v[52:67], v[160:163], v[192:195], v[52:67]
.LaA_nofinalpv_14:
	s_waitcnt lgkmcnt(0)
	s_barrier
	v_mov_b32_e32 v243, v241
	s_nop 1
	v_permlane32_swap_b32 v243, v241
	v_add_f32_e32 v241, v243, v241
	v_rcp_f32_e32 v241, v241
	s_lshl_b32 s6, s9, 14
	s_add_i32 s6, s6, 0x10000
	v_lshlrev_b32_e32 v2, 2, v219
	v_add_u32_e32 v2, s6, v2
	s_cmp_eq_u32 s8, 0
	s_cbranch_scc1 .LaA_comp0_15
	s_nop 7
	s_nop 3
	v_mul_f32_e32 v68, v4, v241
	ds_write_b32 v2, v68 offset:0
	v_mul_f32_e32 v69, v5, v241
	ds_write_b32 v2, v69 offset:256
	v_mul_f32_e32 v68, v6, v241
	ds_write_b32 v2, v68 offset:512
	v_mul_f32_e32 v69, v7, v241
	ds_write_b32 v2, v69 offset:768
	v_mul_f32_e32 v68, v8, v241
	ds_write_b32 v2, v68 offset:1024
	v_mul_f32_e32 v69, v9, v241
	ds_write_b32 v2, v69 offset:1280
	v_mul_f32_e32 v68, v10, v241
	ds_write_b32 v2, v68 offset:1536
	v_mul_f32_e32 v69, v11, v241
	ds_write_b32 v2, v69 offset:1792
	v_mul_f32_e32 v68, v12, v241
	ds_write_b32 v2, v68 offset:2048
	v_mul_f32_e32 v69, v13, v241
	ds_write_b32 v2, v69 offset:2304
	v_mul_f32_e32 v68, v14, v241
	ds_write_b32 v2, v68 offset:2560
	v_mul_f32_e32 v69, v15, v241
	ds_write_b32 v2, v69 offset:2816
	v_mul_f32_e32 v68, v16, v241
	ds_write_b32 v2, v68 offset:3072
	v_mul_f32_e32 v69, v17, v241
	ds_write_b32 v2, v69 offset:3328
	v_mul_f32_e32 v68, v18, v241
	ds_write_b32 v2, v68 offset:3584
	v_mul_f32_e32 v69, v19, v241
	ds_write_b32 v2, v69 offset:3840
	v_mul_f32_e32 v68, v20, v241
	ds_write_b32 v2, v68 offset:4096
	v_mul_f32_e32 v69, v21, v241
	ds_write_b32 v2, v69 offset:4352
	v_mul_f32_e32 v68, v22, v241
	ds_write_b32 v2, v68 offset:4608
	v_mul_f32_e32 v69, v23, v241
	ds_write_b32 v2, v69 offset:4864
	v_mul_f32_e32 v68, v24, v241
	ds_write_b32 v2, v68 offset:5120
	v_mul_f32_e32 v69, v25, v241
	ds_write_b32 v2, v69 offset:5376
	v_mul_f32_e32 v68, v26, v241
	ds_write_b32 v2, v68 offset:5632
	v_mul_f32_e32 v69, v27, v241
	ds_write_b32 v2, v69 offset:5888
	v_mul_f32_e32 v68, v28, v241
	ds_write_b32 v2, v68 offset:6144
	v_mul_f32_e32 v69, v29, v241
	ds_write_b32 v2, v69 offset:6400
	v_mul_f32_e32 v68, v30, v241
	ds_write_b32 v2, v68 offset:6656
	v_mul_f32_e32 v69, v31, v241
	ds_write_b32 v2, v69 offset:6912
	v_mul_f32_e32 v68, v32, v241
	ds_write_b32 v2, v68 offset:7168
	v_mul_f32_e32 v69, v33, v241
	ds_write_b32 v2, v69 offset:7424
	v_mul_f32_e32 v68, v34, v241
	ds_write_b32 v2, v68 offset:7680
	v_mul_f32_e32 v69, v35, v241
	ds_write_b32 v2, v69 offset:7936
	v_mul_f32_e32 v68, v36, v241
	ds_write_b32 v2, v68 offset:8192
	v_mul_f32_e32 v69, v37, v241
	ds_write_b32 v2, v69 offset:8448
	v_mul_f32_e32 v68, v38, v241
	ds_write_b32 v2, v68 offset:8704
	v_mul_f32_e32 v69, v39, v241
	ds_write_b32 v2, v69 offset:8960
	v_mul_f32_e32 v68, v40, v241
	ds_write_b32 v2, v68 offset:9216
; __device__ __forceinline__ void attnA_unit(const P2Ctx& C, int b, int h, int qb) {
;     ...
;     if (comp == 1) {
; #pragma unroll
;         for (int cb = 0; cb < 4; ++cb)
; #pragma unroll
;             for (int r = 0; r < 16; ++r) X2[((qs * 4 + cb) * 16 + r) * 64 + lane] = o[cb][r] * inv;
;     }
;     __syncthreads();
	v_mul_f32_e32 v69, v41, v241
	ds_write_b32 v2, v69 offset:9472
	v_mul_f32_e32 v68, v42, v241
	ds_write_b32 v2, v68 offset:9728
	v_mul_f32_e32 v69, v43, v241
	ds_write_b32 v2, v69 offset:9984
	v_mul_f32_e32 v68, v44, v241
	ds_write_b32 v2, v68 offset:10240
	v_mul_f32_e32 v69, v45, v241
	ds_write_b32 v2, v69 offset:10496
	v_mul_f32_e32 v68, v46, v241
	ds_write_b32 v2, v68 offset:10752
	v_mul_f32_e32 v69, v47, v241
	ds_write_b32 v2, v69 offset:11008
	v_mul_f32_e32 v68, v48, v241
	ds_write_b32 v2, v68 offset:11264
	v_mul_f32_e32 v69, v49, v241
	ds_write_b32 v2, v69 offset:11520
	v_mul_f32_e32 v68, v50, v241
	ds_write_b32 v2, v68 offset:11776
	v_mul_f32_e32 v69, v51, v241
	ds_write_b32 v2, v69 offset:12032
	v_mul_f32_e32 v68, v52, v241
	ds_write_b32 v2, v68 offset:12288
	v_mul_f32_e32 v69, v53, v241
	ds_write_b32 v2, v69 offset:12544
	v_mul_f32_e32 v68, v54, v241
	ds_write_b32 v2, v68 offset:12800
	v_mul_f32_e32 v69, v55, v241
	ds_write_b32 v2, v69 offset:13056
	v_mul_f32_e32 v68, v56, v241
	ds_write_b32 v2, v68 offset:13312
	v_mul_f32_e32 v69, v57, v241
	ds_write_b32 v2, v69 offset:13568
	v_mul_f32_e32 v68, v58, v241
	ds_write_b32 v2, v68 offset:13824
	v_mul_f32_e32 v69, v59, v241
	ds_write_b32 v2, v69 offset:14080
	v_mul_f32_e32 v68, v60, v241
	ds_write_b32 v2, v68 offset:14336
	v_mul_f32_e32 v69, v61, v241
	ds_write_b32 v2, v69 offset:14592
	v_mul_f32_e32 v68, v62, v241
	ds_write_b32 v2, v68 offset:14848
	v_mul_f32_e32 v69, v63, v241
	ds_write_b32 v2, v69 offset:15104
	v_mul_f32_e32 v68, v64, v241
	ds_write_b32 v2, v68 offset:15360
	v_mul_f32_e32 v69, v65, v241
	ds_write_b32 v2, v69 offset:15616
	v_mul_f32_e32 v68, v66, v241
	ds_write_b32 v2, v68 offset:15872
	v_mul_f32_e32 v69, v67, v241
	ds_write_b32 v2, v69 offset:16128
	s_waitcnt lgkmcnt(0)
	s_barrier
	s_branch .LaA_epiend_16
	s_nop 0
	s_nop 0
	s_nop 0
	s_nop 0
	s_nop 0
	s_nop 0
	s_nop 0
	s_nop 0
	s_nop 0
	s_nop 0
	s_nop 0
	s_nop 0
	s_nop 0
	s_nop 0
	s_nop 0
	s_nop 0
	s_nop 0
	s_nop 0
	s_nop 0
	s_nop 0
	s_nop 0
	s_nop 0
	s_nop 0
	s_nop 0
	s_nop 0
	s_nop 0
	s_nop 0
	s_nop 0
	s_nop 0
	s_nop 0
	s_nop 0
	s_nop 0
	s_nop 0
	s_nop 0
	s_nop 0
	s_nop 0
	s_nop 0
	s_nop 0
	s_nop 0
	s_nop 0
	s_nop 0
	s_nop 0
	s_nop 0
	s_nop 0
	s_nop 0
	s_nop 0
	s_nop 0
	s_nop 0
	s_nop 0
	s_nop 0
	s_nop 0
	s_nop 0
	s_nop 0
	s_nop 0
	s_nop 0
	s_nop 0
	s_nop 0
	s_nop 0
	s_nop 0
	s_nop 0
	s_nop 0
	s_nop 0
	s_nop 0
	s_nop 0
	s_nop 0
	s_nop 0
	s_nop 0
	s_nop 0
	s_nop 0
	s_nop 0
	s_nop 0
	s_nop 0
	s_nop 0
	s_nop 0
	s_nop 0
	s_nop 0
	s_nop 0
	s_nop 0
	s_nop 0
	s_nop 0
	s_nop 0
	s_nop 0
	s_nop 0
	s_nop 0
	s_nop 0
	s_nop 0
	s_nop 0
	s_nop 0
	s_nop 0
	s_nop 0
	s_nop 0
	s_nop 0
	s_nop 0
	s_nop 0
	s_nop 0
	s_nop 0
	s_nop 0
	s_nop 0
	s_nop 0
	s_nop 0
	s_nop 0
	s_nop 0
	s_nop 0
	s_nop 0
	s_nop 0
	s_nop 0
	s_nop 0
	s_nop 0
	s_nop 0
	s_nop 0
	s_nop 0
	s_nop 0
	s_nop 0
	s_nop 0
	s_nop 0
	s_nop 0
	s_nop 0
	s_nop 0
	s_nop 0
	s_nop 0
	s_nop 0
	s_nop 0
	s_nop 0
	s_nop 0
	s_nop 0
	s_nop 0
	s_nop 0
	s_nop 0
	s_nop 0
	s_nop 0
	s_nop 0
	s_nop 0
	s_nop 0
	s_nop 0
	s_nop 0
	s_nop 0
	s_nop 0
	s_nop 0
	s_nop 0
	s_nop 0
	s_nop 0
	s_nop 0
	s_nop 0
	s_nop 0
	s_nop 0
	s_nop 0
	s_nop 0
	s_nop 0
	s_nop 0
	s_nop 0
	s_nop 0
	s_nop 0
	s_nop 0
	s_nop 0
	s_nop 0
	s_nop 0
	s_nop 0
	s_nop 0
	s_nop 0
	s_nop 0
	s_nop 0
	s_nop 0
	s_nop 0
	s_nop 0
	s_nop 0
	s_nop 0
	s_nop 0
	s_nop 0
	s_nop 0
	s_nop 0
	s_nop 0
	s_nop 0
	s_nop 0
	s_nop 0
	s_nop 0
	s_nop 0
	s_nop 0
	s_nop 0
	s_nop 0
	s_nop 0
	s_nop 0
	s_nop 0
	s_nop 0
	s_nop 0
	s_nop 0
	s_nop 0
	s_nop 0
	s_nop 0
	s_nop 0
	s_nop 0
	s_nop 0
	s_nop 0
	s_nop 0
	s_nop 0
	s_nop 0
	s_nop 0
	s_nop 0
	s_nop 0
	s_nop 0
	s_nop 0
	s_nop 0
	s_nop 0
	s_nop 0
	s_nop 0
	s_nop 0
	s_nop 0
	s_nop 0
	s_nop 0
	s_nop 0
	s_nop 0
	s_nop 0
	s_nop 0
	s_nop 0
	s_nop 0
	s_nop 0
	s_nop 0
	s_nop 0
	s_nop 0
	s_nop 0
	s_nop 0
	s_nop 0
	s_nop 0
	s_nop 0
	s_nop 0
	s_nop 0
	s_nop 0
	s_nop 0
	s_nop 0
	s_nop 0
	s_nop 0
	s_nop 0
	s_nop 0
	s_nop 0
	s_nop 0
	s_nop 0
	s_nop 0
	s_nop 0
	s_nop 0
	s_nop 0
	s_nop 0
	s_nop 0
	s_nop 0
	s_nop 0
	s_nop 0
	s_nop 0
	s_nop 0
	s_nop 0
	s_nop 0
	s_nop 0
	s_nop 0
	s_nop 0
	s_nop 0
	s_nop 0
	s_nop 0
	s_nop 0
	s_nop 0
	s_nop 0
	s_nop 0
	s_nop 0
	s_nop 0
	s_nop 0
	s_nop 0
	s_nop 0
	s_nop 0
	s_nop 0
	s_nop 0
	s_nop 0
	s_nop 0
	s_nop 0
	s_nop 0
	s_nop 0
	s_nop 0
	s_nop 0
	s_nop 0
	s_nop 0
	s_nop 0
	s_nop 0
	s_nop 0
	s_nop 0
	s_nop 0
	s_nop 0
	s_nop 0
	s_nop 0
	s_nop 0
	s_nop 0
	s_nop 0
	s_nop 0
	s_nop 0
	s_nop 0
	s_nop 0
	s_nop 0
	s_nop 0
	s_nop 0
	s_nop 0
	s_nop 0
	s_nop 0
	s_nop 0
	s_nop 0
	s_nop 0
	s_nop 0
	s_nop 0
	s_nop 0
	s_nop 0
	s_nop 0
	s_nop 0
	s_nop 0
	s_nop 0
	s_nop 0
	s_nop 0
	s_nop 0
	s_nop 0
	s_nop 0
	s_nop 0
	s_nop 0
	s_nop 0
	s_nop 0
	s_nop 0
	s_nop 0
	s_nop 0
	s_nop 0
	s_nop 0
	s_nop 0
	s_nop 0
	s_nop 0
	s_nop 0
	s_nop 0
	s_nop 0
	s_nop 0
	s_nop 0
	s_nop 0
	s_nop 0
	s_nop 0
	s_nop 0
	s_nop 0
	s_nop 0
	s_nop 0
	s_nop 0
	s_nop 0
	s_nop 0
	s_nop 0
	s_nop 0
	s_nop 0
	s_nop 0
	s_nop 0
	s_nop 0
	s_nop 0
	s_nop 0
	s_nop 0
	s_nop 0
	s_nop 0
	s_nop 0
	s_nop 0
	s_nop 0
	s_nop 0
	s_nop 0
	s_nop 0
	s_nop 0
	s_nop 0
	s_nop 0
	s_nop 0
	s_nop 0
	s_nop 0
	s_nop 0
	s_nop 0
	s_nop 0
	s_nop 0
	s_nop 0
	s_nop 0
	s_nop 0
	s_nop 0
	s_nop 0
	s_nop 0
	s_nop 0
	s_nop 0
	s_nop 0
	s_nop 0
	s_nop 0
	s_nop 0
	s_nop 0
	s_nop 0
	s_nop 0
	s_nop 0
	s_nop 0
	s_nop 0
	s_nop 0
	s_nop 0
	s_nop 0
	s_nop 0
	s_nop 0
	s_nop 0
	s_nop 0
	s_nop 0
	s_nop 0
	s_nop 0
	s_nop 0
	s_nop 0
	s_nop 0
	s_nop 0
	s_nop 0
	s_nop 0
	s_nop 0
	s_nop 0
	s_nop 0
	s_nop 0
	s_nop 0
	s_nop 0
	s_nop 0
	s_nop 0
	s_nop 0
	s_nop 0
	s_nop 0
	s_nop 0
	s_nop 0
	s_nop 0
	s_nop 0
	s_nop 0
	s_nop 0
	s_nop 0
	s_nop 0
	s_nop 0
	s_nop 0
	s_nop 0
	s_nop 0
	s_nop 0
	s_nop 0
	s_nop 0
; __device__ __forceinline__ void subln_store(f32x16 (&o)[4], const float* subg, bf16_t* dst  , int lane) {
;     ...
;     f32x4 sg[4][4];
; #pragma unroll
;     for (int cb = 0; cb < 4; ++cb)
; #pragma unroll
;         for (int g = 0; g < 4; ++g) sg[cb][g] = *(const f32x4*)(subg + 32 * cb + 8 * g + 4 * hi);
; __device__ __forceinline__ void attnA_unit(const P2Ctx& C, int b, int h, int qb) {
;     ...
;     if (comp == 0) {
; #pragma unroll
;         for (int cb = 0; cb < 4; ++cb)
; #pragma unroll
;             for (int r = 0; r < 16; ++r) o[cb][r] = o[cb][r] * inv - lam * X2[((qs * 4 + cb) * 16 + r) * 64 + lane];
	s_nop 0
	s_nop 0
	s_nop 0
	s_nop 0
	s_nop 0
	s_nop 0
	s_nop 0
	s_nop 0
	s_nop 0
	s_nop 0
	s_nop 0
	s_nop 0
	s_nop 0
	s_nop 0
	s_nop 0
	s_nop 0
	s_nop 0
	s_nop 0
	s_nop 0
	s_nop 0
	s_nop 0
	s_nop 0
	s_nop 0
	s_nop 0
	s_nop 0
	s_nop 0
	s_nop 0
	s_nop 0
	s_nop 0
	s_nop 0
	s_nop 0
	s_nop 0
	s_nop 0
	s_nop 0
	s_nop 0
	s_nop 0
	s_nop 0
	s_nop 0
	s_nop 0
	s_nop 0
	s_nop 0
	s_nop 0
	s_nop 0
	s_nop 0
	s_nop 0
	s_nop 0
	s_nop 0
	s_nop 0
	s_nop 0
	s_nop 0
	s_nop 0
	s_nop 0
	s_nop 0
	s_nop 0
	s_nop 0
	s_nop 0
	s_nop 0
	s_nop 0
	s_nop 0
	s_nop 0
	s_nop 0
	s_nop 0
	s_nop 0
	s_nop 0
	s_nop 0
	s_nop 0
	s_nop 0
	s_nop 0
	s_nop 0
	s_nop 0
	s_nop 0
	s_nop 0
	s_nop 0
	s_nop 0
	s_nop 0
	s_nop 0
	s_nop 0
	s_nop 0
	s_nop 0
	s_nop 0
	s_nop 0
	s_nop 0
	s_nop 0
	s_nop 0
	s_nop 0
	s_nop 0
	s_nop 0
	s_nop 0
	s_nop 0
	s_nop 0
	s_nop 0
	s_nop 0
	s_nop 0
	s_nop 0
	s_nop 0
	s_nop 0
	s_nop 0
	s_nop 0
	s_nop 0
	s_nop 0
	s_nop 0
	s_nop 0
	s_nop 0
	s_nop 0
	s_nop 0
	s_nop 0
	s_nop 0
	s_nop 0
	s_nop 0
	s_nop 0
	s_nop 0
	s_nop 0
	s_nop 0
	s_nop 0
	s_nop 0
	s_nop 0
	s_nop 0
	s_nop 0
	s_nop 0
	s_nop 0
	s_nop 0
	s_nop 0
	s_nop 0
	s_nop 0
	s_nop 0
	s_nop 0
	s_nop 0
	s_nop 0
	s_nop 0
	s_nop 0
	s_nop 0
	s_nop 0
	s_nop 0
	s_nop 0
	s_nop 0
	s_nop 0
	s_nop 0
	s_nop 0
	s_nop 0
	s_nop 0
	s_nop 0
	s_nop 0
	s_nop 0
	s_nop 0
	s_nop 0
	s_nop 0
	s_nop 0
	s_nop 0
	s_nop 0
	s_nop 0
	s_nop 0
	s_nop 0
	s_nop 0
	s_nop 0
	s_nop 0
	s_nop 0
	s_nop 0
	s_nop 0
	s_nop 0
	s_nop 0
	s_nop 0
	s_nop 0
	s_nop 0
	s_nop 0
	s_nop 0
	s_nop 0
	s_nop 0
	s_nop 0
	s_nop 0
	s_nop 0
	s_nop 0
	s_nop 0
	s_nop 0
	s_nop 0
	s_nop 0
	s_nop 0
	s_nop 0
	s_nop 0
	s_nop 0
	s_nop 0
	s_nop 0
	s_nop 0
	s_nop 0
	s_nop 0
	s_nop 0
	s_nop 0
	s_nop 0
	s_nop 0
	s_nop 0
	s_nop 0
	s_nop 0
	s_nop 0
	s_nop 0
	s_nop 0
	s_nop 0
	s_nop 0
	s_nop 0
	s_nop 0
	s_nop 0
	s_nop 0
	s_nop 0
	s_nop 0
	s_nop 0
	s_nop 0
	s_nop 0
	s_nop 0
	s_nop 0
	s_nop 0
	s_nop 0
	s_nop 0
	s_nop 0
	s_nop 0
	s_nop 0
	s_nop 0
	s_nop 0
	s_nop 0
	s_nop 0
	s_nop 0
	s_nop 0
	s_nop 0
	s_nop 0
	s_nop 0
	s_nop 0
	s_nop 0
	s_nop 0
	s_nop 0
	s_nop 0
	s_nop 0
	s_nop 0
	s_nop 0
	s_nop 0
	s_nop 0
	s_nop 0
	s_nop 0
	s_nop 0
	s_nop 0
	s_nop 0
	s_nop 0
	s_nop 0
	s_nop 0
	s_nop 0
	s_nop 0
	s_nop 0
	s_nop 0
	s_nop 0
	s_nop 0
	s_nop 0
	s_nop 0
	s_nop 0
	s_nop 0
	s_nop 0
	s_nop 0
	s_nop 0
	s_nop 0
	s_nop 0
	s_nop 0
	s_nop 0
	s_nop 0
	s_nop 0
	s_nop 0
	s_nop 0
	s_nop 0
	s_nop 0
	s_nop 0
.LaA_comp0_15:
	v_lshrrev_b32_e32 v242, 5, v219
	v_lshlrev_b32_e32 v242, 4, v242
	v_add_u32_e32 v242, 0x22a00, v242
	ds_read_b128 v[100:103], v242 offset:0
	ds_read_b128 v[104:107], v242 offset:32
	ds_read_b128 v[108:111], v242 offset:64
	ds_read_b128 v[112:115], v242 offset:96
	ds_read_b128 v[116:119], v242 offset:128
	ds_read_b128 v[120:123], v242 offset:160
	ds_read_b128 v[124:127], v242 offset:192
	ds_read_b128 v[128:131], v242 offset:224
	s_waitcnt lgkmcnt(4)
	ds_read_b128 v[132:135], v242 offset:256
	ds_read_b128 v[136:139], v242 offset:288
	ds_read_b128 v[140:143], v242 offset:320
	ds_read_b128 v[144:147], v242 offset:352
	ds_read_b128 v[148:151], v242 offset:384
	ds_read_b128 v[152:155], v242 offset:416
	ds_read_b128 v[156:159], v242 offset:448
	ds_read_b128 v[160:163], v242 offset:480
	s_waitcnt lgkmcnt(6)
	ds_read_b32 v243, v207
	s_nop 7
	s_nop 3
	v_mul_f32_e32 v4, v4, v241
	v_mul_f32_e32 v5, v5, v241
	v_mul_f32_e32 v6, v6, v241
	v_mul_f32_e32 v7, v7, v241
	v_mul_f32_e32 v8, v8, v241
	v_mul_f32_e32 v9, v9, v241
	v_mul_f32_e32 v10, v10, v241
	v_mul_f32_e32 v11, v11, v241
	v_mul_f32_e32 v12, v12, v241
	v_mul_f32_e32 v13, v13, v241
	v_mul_f32_e32 v14, v14, v241
	v_mul_f32_e32 v15, v15, v241
	v_mul_f32_e32 v16, v16, v241
	v_mul_f32_e32 v17, v17, v241
	v_mul_f32_e32 v18, v18, v241
	v_mul_f32_e32 v19, v19, v241
	v_mul_f32_e32 v20, v20, v241
	v_mul_f32_e32 v21, v21, v241
	v_mul_f32_e32 v22, v22, v241
	v_mul_f32_e32 v23, v23, v241
	v_mul_f32_e32 v24, v24, v241
	v_mul_f32_e32 v25, v25, v241
	v_mul_f32_e32 v26, v26, v241
	v_mul_f32_e32 v27, v27, v241
	v_mul_f32_e32 v28, v28, v241
	v_mul_f32_e32 v29, v29, v241
	v_mul_f32_e32 v30, v30, v241
	v_mul_f32_e32 v31, v31, v241
	v_mul_f32_e32 v32, v32, v241
	v_mul_f32_e32 v33, v33, v241
	v_mul_f32_e32 v34, v34, v241
	v_mul_f32_e32 v35, v35, v241
	v_mul_f32_e32 v36, v36, v241
	v_mul_f32_e32 v37, v37, v241
	v_mul_f32_e32 v38, v38, v241
	v_mul_f32_e32 v39, v39, v241
	v_mul_f32_e32 v40, v40, v241
	v_mul_f32_e32 v41, v41, v241
	v_mul_f32_e32 v42, v42, v241
	v_mul_f32_e32 v43, v43, v241
	v_mul_f32_e32 v44, v44, v241
	v_mul_f32_e32 v45, v45, v241
	v_mul_f32_e32 v46, v46, v241
	v_mul_f32_e32 v47, v47, v241
	v_mul_f32_e32 v48, v48, v241
	v_mul_f32_e32 v49, v49, v241
	v_mul_f32_e32 v50, v50, v241
	v_mul_f32_e32 v51, v51, v241
	v_mul_f32_e32 v52, v52, v241
	v_mul_f32_e32 v53, v53, v241
	v_mul_f32_e32 v54, v54, v241
	v_mul_f32_e32 v55, v55, v241
	v_mul_f32_e32 v56, v56, v241
	v_mul_f32_e32 v57, v57, v241
	v_mul_f32_e32 v58, v58, v241
	v_mul_f32_e32 v59, v59, v241
	v_mul_f32_e32 v60, v60, v241
	v_mul_f32_e32 v61, v61, v241
	v_mul_f32_e32 v62, v62, v241
	v_mul_f32_e32 v63, v63, v241
	v_mul_f32_e32 v64, v64, v241
	v_mul_f32_e32 v65, v65, v241
	v_mul_f32_e32 v66, v66, v241
	v_mul_f32_e32 v67, v67, v241
	s_waitcnt lgkmcnt(0)
	s_barrier
; __device__ __forceinline__ void subln_store(f32x16 (&o)[4], const float* subg, bf16_t* dst  , int lane) {
;     const int hi = lane >> 5;
;     float ss = 0.f;
; #pragma unroll
;     for (int cb = 0; cb < 4; ++cb)
; #pragma unroll
;         for (int r = 0; r < 16; ++r) ss += o[cb][r] * o[cb][r];
;     ss += __shfl_xor(ss, 32);
;     const float rstd = (1.0f - LAMBDA_INIT) / sqrtf(ss * (1.0f / 128.0f) + EPS);
; __device__ __forceinline__ void attnA_unit(const P2Ctx& C, int b, int h, int qb) {
;     ...
;             for (int r = 0; r < 16; ++r) o[cb][r] = o[cb][r] * inv - lam * X2[((qs * 4 + cb) * 16 + r) * 64 + lane];
;         subln_store(o, C.a->in[I_SUBG], C.AO + qrow * DM + h * 128, lane);
	ds_read2st64_b32 v[164:165], v2 offset0:0 offset1:1
	ds_read2st64_b32 v[166:167], v2 offset0:2 offset1:3
	ds_read2st64_b32 v[168:169], v2 offset0:4 offset1:5
	ds_read2st64_b32 v[170:171], v2 offset0:6 offset1:7
	ds_read2st64_b32 v[172:173], v2 offset0:8 offset1:9
	ds_read2st64_b32 v[174:175], v2 offset0:10 offset1:11
	ds_read2st64_b32 v[176:177], v2 offset0:12 offset1:13
	ds_read2st64_b32 v[178:179], v2 offset0:14 offset1:15
	ds_read2st64_b32 v[180:181], v2 offset0:16 offset1:17
	ds_read2st64_b32 v[182:183], v2 offset0:18 offset1:19
	ds_read2st64_b32 v[184:185], v2 offset0:20 offset1:21
	ds_read2st64_b32 v[186:187], v2 offset0:22 offset1:23
	ds_read2st64_b32 v[188:189], v2 offset0:24 offset1:25
	ds_read2st64_b32 v[190:191], v2 offset0:26 offset1:27
	ds_read2st64_b32 v[192:193], v2 offset0:28 offset1:29
	s_waitcnt lgkmcnt(8)
	ds_read2st64_b32 v[194:195], v2 offset0:30 offset1:31
	ds_read2st64_b32 v[68:69], v2 offset0:32 offset1:33
	ds_read2st64_b32 v[70:71], v2 offset0:34 offset1:35
	ds_read2st64_b32 v[72:73], v2 offset0:36 offset1:37
	ds_read2st64_b32 v[74:75], v2 offset0:38 offset1:39
	ds_read2st64_b32 v[76:77], v2 offset0:40 offset1:41
	ds_read2st64_b32 v[78:79], v2 offset0:42 offset1:43
	ds_read2st64_b32 v[80:81], v2 offset0:44 offset1:45
	ds_read2st64_b32 v[82:83], v2 offset0:46 offset1:47
	ds_read2st64_b32 v[84:85], v2 offset0:48 offset1:49
	ds_read2st64_b32 v[86:87], v2 offset0:50 offset1:51
	ds_read2st64_b32 v[88:89], v2 offset0:52 offset1:53
	ds_read2st64_b32 v[90:91], v2 offset0:54 offset1:55
	ds_read2st64_b32 v[92:93], v2 offset0:56 offset1:57
	ds_read2st64_b32 v[94:95], v2 offset0:58 offset1:59
	ds_read2st64_b32 v[96:97], v2 offset0:60 offset1:61
	ds_read2st64_b32 v[98:99], v2 offset0:62 offset1:63
	s_waitcnt lgkmcnt(0)
	v_fma_f32 v4, -v243, v164, v4
	v_fma_f32 v5, -v243, v165, v5
	v_fma_f32 v6, -v243, v166, v6
	v_fma_f32 v7, -v243, v167, v7
	v_fma_f32 v8, -v243, v168, v8
	v_fma_f32 v9, -v243, v169, v9
	v_fma_f32 v10, -v243, v170, v10
	v_fma_f32 v11, -v243, v171, v11
	v_fma_f32 v12, -v243, v172, v12
	v_fma_f32 v13, -v243, v173, v13
	v_fma_f32 v14, -v243, v174, v14
	v_fma_f32 v15, -v243, v175, v15
	v_fma_f32 v16, -v243, v176, v16
	v_fma_f32 v17, -v243, v177, v17
	v_fma_f32 v18, -v243, v178, v18
	v_fma_f32 v19, -v243, v179, v19
	v_fma_f32 v20, -v243, v180, v20
	v_fma_f32 v21, -v243, v181, v21
	v_fma_f32 v22, -v243, v182, v22
	v_fma_f32 v23, -v243, v183, v23
	v_fma_f32 v24, -v243, v184, v24
	v_fma_f32 v25, -v243, v185, v25
	v_fma_f32 v26, -v243, v186, v26
	v_fma_f32 v27, -v243, v187, v27
	v_fma_f32 v28, -v243, v188, v28
	v_fma_f32 v29, -v243, v189, v29
	v_fma_f32 v30, -v243, v190, v30
	v_fma_f32 v31, -v243, v191, v31
	v_fma_f32 v32, -v243, v192, v32
	v_fma_f32 v33, -v243, v193, v33
	v_fma_f32 v34, -v243, v194, v34
	v_fma_f32 v35, -v243, v195, v35
	v_fma_f32 v36, -v243, v68, v36
	v_fma_f32 v37, -v243, v69, v37
	v_fma_f32 v38, -v243, v70, v38
	v_fma_f32 v39, -v243, v71, v39
	v_fma_f32 v40, -v243, v72, v40
	v_fma_f32 v41, -v243, v73, v41
	v_fma_f32 v42, -v243, v74, v42
	v_fma_f32 v43, -v243, v75, v43
	v_fma_f32 v44, -v243, v76, v44
	v_fma_f32 v45, -v243, v77, v45
	v_fma_f32 v46, -v243, v78, v46
	v_fma_f32 v47, -v243, v79, v47
	v_fma_f32 v48, -v243, v80, v48
	v_fma_f32 v49, -v243, v81, v49
	v_fma_f32 v50, -v243, v82, v50
	v_fma_f32 v51, -v243, v83, v51
	v_fma_f32 v52, -v243, v84, v52
	v_fma_f32 v53, -v243, v85, v53
	v_fma_f32 v54, -v243, v86, v54
	v_fma_f32 v55, -v243, v87, v55
	v_fma_f32 v56, -v243, v88, v56
	v_fma_f32 v57, -v243, v89, v57
	v_fma_f32 v58, -v243, v90, v58
	v_fma_f32 v59, -v243, v91, v59
	v_fma_f32 v60, -v243, v92, v60
	v_fma_f32 v61, -v243, v93, v61
	v_fma_f32 v62, -v243, v94, v62
	v_fma_f32 v63, -v243, v95, v63
	v_fma_f32 v64, -v243, v96, v64
	v_fma_f32 v65, -v243, v97, v65
	v_fma_f32 v66, -v243, v98, v66
	v_fma_f32 v67, -v243, v99, v67
	v_mul_f32_e32 v245, v4, v4
	v_fmac_f32_e32 v245, v5, v5
	v_fmac_f32_e32 v245, v6, v6
	v_fmac_f32_e32 v245, v7, v7
	v_fmac_f32_e32 v245, v8, v8
	v_fmac_f32_e32 v245, v9, v9
	v_fmac_f32_e32 v245, v10, v10
	v_fmac_f32_e32 v245, v11, v11
	v_fmac_f32_e32 v245, v12, v12
	v_fmac_f32_e32 v245, v13, v13
	v_fmac_f32_e32 v245, v14, v14
	v_fmac_f32_e32 v245, v15, v15
	v_fmac_f32_e32 v245, v16, v16
	v_fmac_f32_e32 v245, v17, v17
	v_fmac_f32_e32 v245, v18, v18
	v_fmac_f32_e32 v245, v19, v19
	v_fmac_f32_e32 v245, v20, v20
	v_fmac_f32_e32 v245, v21, v21
	v_fmac_f32_e32 v245, v22, v22
	v_fmac_f32_e32 v245, v23, v23
	v_fmac_f32_e32 v245, v24, v24
	v_fmac_f32_e32 v245, v25, v25
	v_fmac_f32_e32 v245, v26, v26
	v_fmac_f32_e32 v245, v27, v27
	v_fmac_f32_e32 v245, v28, v28
	v_fmac_f32_e32 v245, v29, v29
	v_fmac_f32_e32 v245, v30, v30
	v_fmac_f32_e32 v245, v31, v31
	v_fmac_f32_e32 v245, v32, v32
	v_fmac_f32_e32 v245, v33, v33
	v_fmac_f32_e32 v245, v34, v34
	v_fmac_f32_e32 v245, v35, v35
	v_fmac_f32_e32 v245, v36, v36
	v_fmac_f32_e32 v245, v37, v37
	v_fmac_f32_e32 v245, v38, v38
	v_fmac_f32_e32 v245, v39, v39
	v_fmac_f32_e32 v245, v40, v40
	v_fmac_f32_e32 v245, v41, v41
	v_fmac_f32_e32 v245, v42, v42
	v_fmac_f32_e32 v245, v43, v43
	v_fmac_f32_e32 v245, v44, v44
	v_fmac_f32_e32 v245, v45, v45
	v_fmac_f32_e32 v245, v46, v46
	v_fmac_f32_e32 v245, v47, v47
	v_fmac_f32_e32 v245, v48, v48
	v_fmac_f32_e32 v245, v49, v49
	v_fmac_f32_e32 v245, v50, v50
	v_fmac_f32_e32 v245, v51, v51
	v_fmac_f32_e32 v245, v52, v52
	v_fmac_f32_e32 v245, v53, v53
	v_fmac_f32_e32 v245, v54, v54
	v_fmac_f32_e32 v245, v55, v55
	v_fmac_f32_e32 v245, v56, v56
	v_fmac_f32_e32 v245, v57, v57
	v_fmac_f32_e32 v245, v58, v58
	v_fmac_f32_e32 v245, v59, v59
	v_fmac_f32_e32 v245, v60, v60
	v_fmac_f32_e32 v245, v61, v61
	v_fmac_f32_e32 v245, v62, v62
	v_fmac_f32_e32 v245, v63, v63
	v_fmac_f32_e32 v245, v64, v64
	v_fmac_f32_e32 v245, v65, v65
	v_fmac_f32_e32 v245, v66, v66
	v_fmac_f32_e32 v245, v67, v67
	v_mov_b32_e32 v246, v245
	s_nop 1
	v_permlane32_swap_b32 v246, v245
	v_add_f32_e32 v245, v246, v245
	v_mov_b32_e32 v246, 0x3c000000
	v_fmaak_f32 v245, v245, v246, 0x358637bd
	v_rsq_f32_e32 v245, v245
	s_nop 0
	v_mul_f32_e32 v245, 0x3f4ccccd, v245
	s_lshl_b32 s6, s11, 11
	s_add_i32 s6, s6, s15
	s_lshl_b32 s6, s6, 11
	s_lshl_b32 s7, s81, 1
	s_add_i32 s6, s6, s7
	s_add_u32 s20, s70, s6
	s_addc_u32 s21, s71, 0
	v_and_b32_e32 v242, 31, v219
	v_lshlrev_b32_e32 v242, 11, v242
	v_lshrrev_b32_e32 v243, 5, v219
	v_lshl_add_u32 v242, v243, 3, v242
	s_waitcnt vmcnt(0)
; __device__ __forceinline__ unsigned pk_bf16(float lo, float hi) { f32x2 v = {lo, hi}; bf16x2_t b = __builtin_convertvector(v, bf16x2_t); return __builtin_bit_cast(unsigned, b); }
; __device__ __forceinline__ void subln_store(f32x16 (&o)[4], const float* subg, bf16_t* dst  , int lane) {
;     ...
;     for (int cb = 0; cb < 4; ++cb)
; #pragma unroll
;         for (int g = 0; g < 4; ++g) { const int dv0 = 32 * cb + 8 * g + 4 * hi; const f32x4 s4 = sg[cb][g];
;             u32x2 w; w.x = pk_bf16(o[cb][4 * g + 0] * rstd * s4[0], o[cb][4 * g + 1] * rstd * s4[1]); w.y = pk_bf16(o[cb][4 * g + 2] * rstd * s4[2], o[cb][4 * g + 3] * rstd * s4[3]);
;             *(u32x2*)(dst + dv0) = w; }
	v_mul_f32_e32 v4, v4, v245
	v_mul_f32_e32 v5, v5, v245
	v_mul_f32_e32 v6, v6, v245
	v_mul_f32_e32 v7, v7, v245
	v_mul_f32_e32 v4, v4, v100
	v_mul_f32_e32 v5, v5, v101
	v_mul_f32_e32 v6, v6, v102
	v_mul_f32_e32 v7, v7, v103
	v_cvt_pk_bf16_f32 v68, v4, v5
	v_cvt_pk_bf16_f32 v69, v6, v7
	global_store_dwordx2 v242, v[68:69], s[20:21] offset:0
	v_mul_f32_e32 v8, v8, v245
	v_mul_f32_e32 v9, v9, v245
	v_mul_f32_e32 v10, v10, v245
	v_mul_f32_e32 v11, v11, v245
	v_mul_f32_e32 v8, v8, v104
	v_mul_f32_e32 v9, v9, v105
	v_mul_f32_e32 v10, v10, v106
	v_mul_f32_e32 v11, v11, v107
	v_cvt_pk_bf16_f32 v70, v8, v9
	v_cvt_pk_bf16_f32 v71, v10, v11
	global_store_dwordx2 v242, v[70:71], s[20:21] offset:16
	v_mul_f32_e32 v12, v12, v245
	v_mul_f32_e32 v13, v13, v245
	v_mul_f32_e32 v14, v14, v245
	v_mul_f32_e32 v15, v15, v245
	v_mul_f32_e32 v12, v12, v108
	v_mul_f32_e32 v13, v13, v109
	v_mul_f32_e32 v14, v14, v110
	v_mul_f32_e32 v15, v15, v111
	v_cvt_pk_bf16_f32 v68, v12, v13
	v_cvt_pk_bf16_f32 v69, v14, v15
	global_store_dwordx2 v242, v[68:69], s[20:21] offset:32
	v_mul_f32_e32 v16, v16, v245
	v_mul_f32_e32 v17, v17, v245
	v_mul_f32_e32 v18, v18, v245
	v_mul_f32_e32 v19, v19, v245
	v_mul_f32_e32 v16, v16, v112
	v_mul_f32_e32 v17, v17, v113
	v_mul_f32_e32 v18, v18, v114
	v_mul_f32_e32 v19, v19, v115
	v_cvt_pk_bf16_f32 v70, v16, v17
	v_cvt_pk_bf16_f32 v71, v18, v19
	global_store_dwordx2 v242, v[70:71], s[20:21] offset:48
	v_mul_f32_e32 v20, v20, v245
	v_mul_f32_e32 v21, v21, v245
	v_mul_f32_e32 v22, v22, v245
	v_mul_f32_e32 v23, v23, v245
	v_mul_f32_e32 v20, v20, v116
	v_mul_f32_e32 v21, v21, v117
	v_mul_f32_e32 v22, v22, v118
	v_mul_f32_e32 v23, v23, v119
	v_cvt_pk_bf16_f32 v68, v20, v21
	v_cvt_pk_bf16_f32 v69, v22, v23
	global_store_dwordx2 v242, v[68:69], s[20:21] offset:64
	v_mul_f32_e32 v24, v24, v245
	v_mul_f32_e32 v25, v25, v245
	v_mul_f32_e32 v26, v26, v245
	v_mul_f32_e32 v27, v27, v245
	v_mul_f32_e32 v24, v24, v120
	v_mul_f32_e32 v25, v25, v121
	v_mul_f32_e32 v26, v26, v122
	v_mul_f32_e32 v27, v27, v123
	v_cvt_pk_bf16_f32 v70, v24, v25
	v_cvt_pk_bf16_f32 v71, v26, v27
	global_store_dwordx2 v242, v[70:71], s[20:21] offset:80
	v_mul_f32_e32 v28, v28, v245
	v_mul_f32_e32 v29, v29, v245
	v_mul_f32_e32 v30, v30, v245
	v_mul_f32_e32 v31, v31, v245
	v_mul_f32_e32 v28, v28, v124
	v_mul_f32_e32 v29, v29, v125
	v_mul_f32_e32 v30, v30, v126
	v_mul_f32_e32 v31, v31, v127
	v_cvt_pk_bf16_f32 v68, v28, v29
	v_cvt_pk_bf16_f32 v69, v30, v31
	global_store_dwordx2 v242, v[68:69], s[20:21] offset:96
	v_mul_f32_e32 v32, v32, v245
	v_mul_f32_e32 v33, v33, v245
	v_mul_f32_e32 v34, v34, v245
	v_mul_f32_e32 v35, v35, v245
	v_mul_f32_e32 v32, v32, v128
	v_mul_f32_e32 v33, v33, v129
	v_mul_f32_e32 v34, v34, v130
	v_mul_f32_e32 v35, v35, v131
	v_cvt_pk_bf16_f32 v70, v32, v33
	v_cvt_pk_bf16_f32 v71, v34, v35
	global_store_dwordx2 v242, v[70:71], s[20:21] offset:112
	v_mul_f32_e32 v36, v36, v245
	v_mul_f32_e32 v37, v37, v245
	v_mul_f32_e32 v38, v38, v245
	v_mul_f32_e32 v39, v39, v245
	v_mul_f32_e32 v36, v36, v132
	v_mul_f32_e32 v37, v37, v133
	v_mul_f32_e32 v38, v38, v134
	v_mul_f32_e32 v39, v39, v135
	v_cvt_pk_bf16_f32 v68, v36, v37
	v_cvt_pk_bf16_f32 v69, v38, v39
	global_store_dwordx2 v242, v[68:69], s[20:21] offset:128
	v_mul_f32_e32 v40, v40, v245
	v_mul_f32_e32 v41, v41, v245
	v_mul_f32_e32 v42, v42, v245
	v_mul_f32_e32 v43, v43, v245
	v_mul_f32_e32 v40, v40, v136
	v_mul_f32_e32 v41, v41, v137
	v_mul_f32_e32 v42, v42, v138
	v_mul_f32_e32 v43, v43, v139
	v_cvt_pk_bf16_f32 v70, v40, v41
	v_cvt_pk_bf16_f32 v71, v42, v43
	global_store_dwordx2 v242, v[70:71], s[20:21] offset:144
	v_mul_f32_e32 v44, v44, v245
	v_mul_f32_e32 v45, v45, v245
	v_mul_f32_e32 v46, v46, v245
	v_mul_f32_e32 v47, v47, v245
	v_mul_f32_e32 v44, v44, v140
	v_mul_f32_e32 v45, v45, v141
	v_mul_f32_e32 v46, v46, v142
	v_mul_f32_e32 v47, v47, v143
	v_cvt_pk_bf16_f32 v68, v44, v45
	v_cvt_pk_bf16_f32 v69, v46, v47
	global_store_dwordx2 v242, v[68:69], s[20:21] offset:160
	v_mul_f32_e32 v48, v48, v245
	v_mul_f32_e32 v49, v49, v245
	v_mul_f32_e32 v50, v50, v245
	v_mul_f32_e32 v51, v51, v245
	v_mul_f32_e32 v48, v48, v144
	v_mul_f32_e32 v49, v49, v145
	v_mul_f32_e32 v50, v50, v146
	v_mul_f32_e32 v51, v51, v147
	v_cvt_pk_bf16_f32 v70, v48, v49
	v_cvt_pk_bf16_f32 v71, v50, v51
	global_store_dwordx2 v242, v[70:71], s[20:21] offset:176
	v_mul_f32_e32 v52, v52, v245
	v_mul_f32_e32 v53, v53, v245
	v_mul_f32_e32 v54, v54, v245
	v_mul_f32_e32 v55, v55, v245
	v_mul_f32_e32 v52, v52, v148
	v_mul_f32_e32 v53, v53, v149
	v_mul_f32_e32 v54, v54, v150
	v_mul_f32_e32 v55, v55, v151
	v_cvt_pk_bf16_f32 v68, v52, v53
	v_cvt_pk_bf16_f32 v69, v54, v55
	global_store_dwordx2 v242, v[68:69], s[20:21] offset:192
	v_mul_f32_e32 v56, v56, v245
	v_mul_f32_e32 v57, v57, v245
	v_mul_f32_e32 v58, v58, v245
	v_mul_f32_e32 v59, v59, v245
	v_mul_f32_e32 v56, v56, v152
	v_mul_f32_e32 v57, v57, v153
	v_mul_f32_e32 v58, v58, v154
	v_mul_f32_e32 v59, v59, v155
	v_cvt_pk_bf16_f32 v70, v56, v57
	v_cvt_pk_bf16_f32 v71, v58, v59
	global_store_dwordx2 v242, v[70:71], s[20:21] offset:208
	v_mul_f32_e32 v60, v60, v245
	v_mul_f32_e32 v61, v61, v245
	v_mul_f32_e32 v62, v62, v245
	v_mul_f32_e32 v63, v63, v245
	v_mul_f32_e32 v60, v60, v156
	v_mul_f32_e32 v61, v61, v157
	v_mul_f32_e32 v62, v62, v158
	v_mul_f32_e32 v63, v63, v159
	v_cvt_pk_bf16_f32 v68, v60, v61
	v_cvt_pk_bf16_f32 v69, v62, v63
	global_store_dwordx2 v242, v[68:69], s[20:21] offset:224
	v_mul_f32_e32 v64, v64, v245
	v_mul_f32_e32 v65, v65, v245
	v_mul_f32_e32 v66, v66, v245
	v_mul_f32_e32 v67, v67, v245
	v_mul_f32_e32 v64, v64, v160
	v_mul_f32_e32 v65, v65, v161
	v_mul_f32_e32 v66, v66, v162
	v_mul_f32_e32 v67, v67, v163
	v_cvt_pk_bf16_f32 v70, v64, v65
	v_cvt_pk_bf16_f32 v71, v66, v67
	global_store_dwordx2 v242, v[70:71], s[20:21] offset:240
